# post-solve rewrite restored with the missing LDS wait (the sunk FMAs read the last column load only after lgkmcnt(0)); passes the emission-delay robustness probe
# speedup vs baseline: 1.0007x; 1.0007x over previous
.LBB0_216:
	s_and_b64 vcc, exec, s[28:29]
	s_cbranch_vccz .LBB0_236
	s_setprio 2
	v_lshlrev_b32_e32 v3, 2, v1
	v_ashrrev_i32_e32 v33, 7, v1
	s_movk_i32 s6, 0x2080
	v_and_b32_e32 v32, 12, v3
	v_ashrrev_i32_e32 v14, 2, v1
	v_mul_lo_u32 v2, v33, s6
	v_lshlrev_b32_e32 v19, 2, v32
	v_readlane_b32 s6, v253, 51
	v_and_b32_e32 v15, 31, v14
	v_cmp_eq_u32_e32 vcc, v32, v15
	v_add3_u32 v6, s6, v2, v19
	ds_read_b128 v[150:153], v6
	ds_read_b128 v[154:157], v6 offset:64
	ds_read_b128 v[158:161], v6 offset:256
	ds_read_b128 v[162:165], v6 offset:320
	ds_read_b128 v[166:169], v6 offset:512
	ds_read_b128 v[170:173], v6 offset:576
	ds_read_b128 v[174:177], v6 offset:768
	ds_read_b128 v[178:181], v6 offset:832
	ds_read_b128 v[182:185], v6 offset:1024
	ds_read_b128 v[186:189], v6 offset:1088
	ds_read_b128 v[190:193], v6 offset:1280
	ds_read_b128 v[194:197], v6 offset:1344
	v_cndmask_b32_e64 v12, 0, 1.0, vcc
	v_or_b32_e32 v31, 1, v32
	v_cmp_eq_u32_e32 vcc, v31, v15
	v_or_b32_e32 v30, 2, v32
	s_nop 0
	v_cndmask_b32_e64 v13, 0, 1.0, vcc
	v_cmp_eq_u32_e32 vcc, v30, v15
	v_or_b32_e32 v29, 3, v32
	v_or_b32_e32 v28, 16, v32
	v_cndmask_b32_e64 v16, 0, 1.0, vcc
	v_cmp_eq_u32_e32 vcc, v29, v15
	s_waitcnt vmcnt(1)
	s_nop 0
	v_cndmask_b32_e64 v17, 0, 1.0, vcc
	v_cmp_eq_u32_e32 vcc, v28, v15
	v_or_b32_e32 v27, 17, v32
	v_or_b32_e32 v26, 18, v32
	v_cndmask_b32_e64 v22, 0, 1.0, vcc
	v_cmp_eq_u32_e32 vcc, v27, v15
	s_nop 1
	v_cndmask_b32_e64 v23, 0, 1.0, vcc
	v_cmp_eq_u32_e32 vcc, v26, v15
	v_or_b32_e32 v21, 19, v32
	s_nop 0
	v_cndmask_b32_e64 v114, 0, 1.0, vcc
	v_cmp_eq_u32_e32 vcc, v21, v15
	v_mov_b32_dpp v18, v12 quad_perm:[0,0,0,0] row_mask:0xf bank_mask:0xf
	s_nop 0
	v_cndmask_b32_e64 v115, 0, 1.0, vcc
	s_waitcnt lgkmcnt(11)
	v_pk_fma_f32 v[12:13], v[150:151], v[18:19], v[12:13] op_sel_hi:[1,0,1] neg_lo:[0,1,0] neg_hi:[0,1,0]
	v_pk_fma_f32 v[16:17], v[152:153], v[18:19], v[16:17] op_sel_hi:[1,0,1] neg_lo:[0,1,0] neg_hi:[0,1,0]
	ds_read_b128 v[150:153], v6 offset:1536
	s_waitcnt lgkmcnt(11)
	v_pk_fma_f32 v[22:23], v[154:155], v[18:19], v[22:23] op_sel_hi:[1,0,1] neg_lo:[0,1,0] neg_hi:[0,1,0]
	v_pk_fma_f32 v[114:115], v[156:157], v[18:19], v[114:115] op_sel_hi:[1,0,1] neg_lo:[0,1,0] neg_hi:[0,1,0]
	ds_read_b128 v[154:157], v6 offset:1600
	v_mov_b32_e32 v20, v131
	v_readlane_b32 s6, v253, 52
	v_mov_b32_dpp v18, v13 quad_perm:[0,0,0,0] row_mask:0xf bank_mask:0xf
	s_waitcnt lgkmcnt(11)
	v_pk_fma_f32 v[16:17], v[160:161], v[18:19], v[16:17] op_sel_hi:[1,0,1] neg_lo:[0,1,0] neg_hi:[0,1,0]
	v_pk_fma_f32 v[12:13], v[158:159], v[18:19], v[12:13] op_sel_hi:[1,0,1] neg_lo:[0,1,0] neg_hi:[0,1,0]
	ds_read_b128 v[158:161], v6 offset:1792
	s_waitcnt lgkmcnt(11)
	v_pk_fma_f32 v[114:115], v[164:165], v[18:19], v[114:115] op_sel_hi:[1,0,1] neg_lo:[0,1,0] neg_hi:[0,1,0]
	v_pk_fma_f32 v[22:23], v[162:163], v[18:19], v[22:23] op_sel_hi:[1,0,1] neg_lo:[0,1,0] neg_hi:[0,1,0]
	ds_read_b128 v[162:165], v6 offset:1856
	s_movk_i32 s8, 0x48
	v_cmp_eq_u32_e32 vcc, 1, v33
	v_mov_b32_dpp v18, v16 quad_perm:[0,0,0,0] row_mask:0xf bank_mask:0xf
	s_waitcnt lgkmcnt(11)
	v_pk_fma_f32 v[16:17], v[168:169], v[18:19], v[16:17] op_sel_hi:[1,0,1] neg_lo:[0,1,0] neg_hi:[0,1,0]
	v_pk_fma_f32 v[12:13], v[166:167], v[18:19], v[12:13] op_sel_hi:[1,0,1] neg_lo:[0,1,0] neg_hi:[0,1,0]
	ds_read_b128 v[166:169], v6 offset:2048
	s_waitcnt lgkmcnt(11)
	v_pk_fma_f32 v[114:115], v[172:173], v[18:19], v[114:115] op_sel_hi:[1,0,1] neg_lo:[0,1,0] neg_hi:[0,1,0]
	v_pk_fma_f32 v[22:23], v[170:171], v[18:19], v[22:23] op_sel_hi:[1,0,1] neg_lo:[0,1,0] neg_hi:[0,1,0]
	ds_read_b128 v[170:173], v6 offset:2112
	v_mov_b32_dpp v18, v17 quad_perm:[0,0,0,0] row_mask:0xf bank_mask:0xf
	s_waitcnt lgkmcnt(11)
	v_pk_fma_f32 v[12:13], v[174:175], v[18:19], v[12:13] op_sel_hi:[1,0,1] neg_lo:[0,1,0] neg_hi:[0,1,0]
	v_pk_fma_f32 v[16:17], v[176:177], v[18:19], v[16:17] op_sel_hi:[1,0,1] neg_lo:[0,1,0] neg_hi:[0,1,0]
	ds_read_b128 v[174:177], v6 offset:2304
	s_waitcnt lgkmcnt(11)
	v_pk_fma_f32 v[114:115], v[180:181], v[18:19], v[114:115] op_sel_hi:[1,0,1] neg_lo:[0,1,0] neg_hi:[0,1,0]
	v_pk_fma_f32 v[22:23], v[178:179], v[18:19], v[22:23] op_sel_hi:[1,0,1] neg_lo:[0,1,0] neg_hi:[0,1,0]
	ds_read_b128 v[178:181], v6 offset:2368
	v_mov_b32_dpp v18, v12 quad_perm:[1,1,1,1] row_mask:0xf bank_mask:0xf
	s_waitcnt lgkmcnt(11)
	v_pk_fma_f32 v[12:13], v[182:183], v[18:19], v[12:13] op_sel_hi:[1,0,1] neg_lo:[0,1,0] neg_hi:[0,1,0]
	v_pk_fma_f32 v[16:17], v[184:185], v[18:19], v[16:17] op_sel_hi:[1,0,1] neg_lo:[0,1,0] neg_hi:[0,1,0]
	ds_read_b128 v[182:185], v6 offset:2560
	s_waitcnt lgkmcnt(11)
	v_pk_fma_f32 v[22:23], v[186:187], v[18:19], v[22:23] op_sel_hi:[1,0,1] neg_lo:[0,1,0] neg_hi:[0,1,0]
	v_pk_fma_f32 v[114:115], v[188:189], v[18:19], v[114:115] op_sel_hi:[1,0,1] neg_lo:[0,1,0] neg_hi:[0,1,0]
	ds_read_b128 v[186:189], v6 offset:2624
	v_mov_b32_dpp v18, v13 quad_perm:[1,1,1,1] row_mask:0xf bank_mask:0xf
	s_waitcnt lgkmcnt(11)
	v_pk_fma_f32 v[16:17], v[192:193], v[18:19], v[16:17] op_sel_hi:[1,0,1] neg_lo:[0,1,0] neg_hi:[0,1,0]
	v_pk_fma_f32 v[12:13], v[190:191], v[18:19], v[12:13] op_sel_hi:[1,0,1] neg_lo:[0,1,0] neg_hi:[0,1,0]
	ds_read_b128 v[190:193], v6 offset:2816
	s_waitcnt lgkmcnt(11)
	v_pk_fma_f32 v[114:115], v[196:197], v[18:19], v[114:115] op_sel_hi:[1,0,1] neg_lo:[0,1,0] neg_hi:[0,1,0]
	v_pk_fma_f32 v[22:23], v[194:195], v[18:19], v[22:23] op_sel_hi:[1,0,1] neg_lo:[0,1,0] neg_hi:[0,1,0]
	ds_read_b128 v[194:197], v6 offset:2880
	v_mov_b32_dpp v18, v16 quad_perm:[1,1,1,1] row_mask:0xf bank_mask:0xf
	s_waitcnt lgkmcnt(11)
	v_pk_fma_f32 v[16:17], v[152:153], v[18:19], v[16:17] op_sel_hi:[1,0,1] neg_lo:[0,1,0] neg_hi:[0,1,0]
	v_pk_fma_f32 v[12:13], v[150:151], v[18:19], v[12:13] op_sel_hi:[1,0,1] neg_lo:[0,1,0] neg_hi:[0,1,0]
	ds_read_b128 v[150:153], v6 offset:3072
	s_waitcnt lgkmcnt(11)
	v_pk_fma_f32 v[22:23], v[154:155], v[18:19], v[22:23] op_sel_hi:[1,0,1] neg_lo:[0,1,0] neg_hi:[0,1,0]
	v_pk_fma_f32 v[114:115], v[156:157], v[18:19], v[114:115] op_sel_hi:[1,0,1] neg_lo:[0,1,0] neg_hi:[0,1,0]
	ds_read_b128 v[154:157], v6 offset:3136
	v_mov_b32_dpp v18, v17 quad_perm:[1,1,1,1] row_mask:0xf bank_mask:0xf
	s_waitcnt lgkmcnt(11)
	v_pk_fma_f32 v[12:13], v[158:159], v[18:19], v[12:13] op_sel_hi:[1,0,1] neg_lo:[0,1,0] neg_hi:[0,1,0]
	v_pk_fma_f32 v[16:17], v[160:161], v[18:19], v[16:17] op_sel_hi:[1,0,1] neg_lo:[0,1,0] neg_hi:[0,1,0]
	ds_read_b128 v[158:161], v6 offset:3328
	s_waitcnt lgkmcnt(11)
	v_pk_fma_f32 v[114:115], v[164:165], v[18:19], v[114:115] op_sel_hi:[1,0,1] neg_lo:[0,1,0] neg_hi:[0,1,0]
	v_pk_fma_f32 v[22:23], v[162:163], v[18:19], v[22:23] op_sel_hi:[1,0,1] neg_lo:[0,1,0] neg_hi:[0,1,0]
	ds_read_b128 v[162:165], v6 offset:3392
	v_mov_b32_dpp v18, v12 quad_perm:[2,2,2,2] row_mask:0xf bank_mask:0xf
	s_waitcnt lgkmcnt(11)
	v_pk_fma_f32 v[12:13], v[166:167], v[18:19], v[12:13] op_sel_hi:[1,0,1] neg_lo:[0,1,0] neg_hi:[0,1,0]
	v_pk_fma_f32 v[16:17], v[168:169], v[18:19], v[16:17] op_sel_hi:[1,0,1] neg_lo:[0,1,0] neg_hi:[0,1,0]
	ds_read_b128 v[166:169], v6 offset:3584
	s_waitcnt lgkmcnt(11)
	v_pk_fma_f32 v[22:23], v[170:171], v[18:19], v[22:23] op_sel_hi:[1,0,1] neg_lo:[0,1,0] neg_hi:[0,1,0]
	v_pk_fma_f32 v[114:115], v[172:173], v[18:19], v[114:115] op_sel_hi:[1,0,1] neg_lo:[0,1,0] neg_hi:[0,1,0]
	ds_read_b128 v[170:173], v6 offset:3648
	v_mov_b32_dpp v18, v13 quad_perm:[2,2,2,2] row_mask:0xf bank_mask:0xf
	s_waitcnt lgkmcnt(11)
	v_pk_fma_f32 v[16:17], v[176:177], v[18:19], v[16:17] op_sel_hi:[1,0,1] neg_lo:[0,1,0] neg_hi:[0,1,0]
	v_pk_fma_f32 v[12:13], v[174:175], v[18:19], v[12:13] op_sel_hi:[1,0,1] neg_lo:[0,1,0] neg_hi:[0,1,0]
	ds_read_b128 v[174:177], v6 offset:3840
	s_waitcnt lgkmcnt(11)
	v_pk_fma_f32 v[114:115], v[180:181], v[18:19], v[114:115] op_sel_hi:[1,0,1] neg_lo:[0,1,0] neg_hi:[0,1,0]
	v_pk_fma_f32 v[22:23], v[178:179], v[18:19], v[22:23] op_sel_hi:[1,0,1] neg_lo:[0,1,0] neg_hi:[0,1,0]
	ds_read_b128 v[178:181], v6 offset:3904
	v_mov_b32_dpp v18, v16 quad_perm:[2,2,2,2] row_mask:0xf bank_mask:0xf
	s_waitcnt lgkmcnt(11)
	v_pk_fma_f32 v[16:17], v[184:185], v[18:19], v[16:17] op_sel_hi:[1,0,1] neg_lo:[0,1,0] neg_hi:[0,1,0]
	v_pk_fma_f32 v[12:13], v[182:183], v[18:19], v[12:13] op_sel_hi:[1,0,1] neg_lo:[0,1,0] neg_hi:[0,1,0]
	ds_read_b128 v[182:185], v6 offset:4160
	s_waitcnt lgkmcnt(11)
	v_pk_fma_f32 v[22:23], v[186:187], v[18:19], v[22:23] op_sel_hi:[1,0,1] neg_lo:[0,1,0] neg_hi:[0,1,0]
	v_pk_fma_f32 v[114:115], v[188:189], v[18:19], v[114:115] op_sel_hi:[1,0,1] neg_lo:[0,1,0] neg_hi:[0,1,0]
	ds_read_b128 v[186:189], v6 offset:4416
	v_mov_b32_dpp v18, v17 quad_perm:[2,2,2,2] row_mask:0xf bank_mask:0xf
	s_waitcnt lgkmcnt(11)
	v_pk_fma_f32 v[12:13], v[190:191], v[18:19], v[12:13] op_sel_hi:[1,0,1] neg_lo:[0,1,0] neg_hi:[0,1,0]
	v_pk_fma_f32 v[16:17], v[192:193], v[18:19], v[16:17] op_sel_hi:[1,0,1] neg_lo:[0,1,0] neg_hi:[0,1,0]
	ds_read_b128 v[190:193], v6 offset:4672
	s_waitcnt lgkmcnt(11)
	v_pk_fma_f32 v[114:115], v[196:197], v[18:19], v[114:115] op_sel_hi:[1,0,1] neg_lo:[0,1,0] neg_hi:[0,1,0]
	v_pk_fma_f32 v[22:23], v[194:195], v[18:19], v[22:23] op_sel_hi:[1,0,1] neg_lo:[0,1,0] neg_hi:[0,1,0]
	ds_read_b128 v[194:197], v6 offset:4928
	v_mov_b32_dpp v18, v12 quad_perm:[3,3,3,3] row_mask:0xf bank_mask:0xf
	s_waitcnt lgkmcnt(11)
	v_pk_fma_f32 v[12:13], v[150:151], v[18:19], v[12:13] op_sel_hi:[1,0,1] neg_lo:[0,1,0] neg_hi:[0,1,0]
	v_pk_fma_f32 v[16:17], v[152:153], v[18:19], v[16:17] op_sel_hi:[1,0,1] neg_lo:[0,1,0] neg_hi:[0,1,0]
	ds_read_b128 v[150:153], v6 offset:5184
	s_waitcnt lgkmcnt(11)
	v_pk_fma_f32 v[22:23], v[154:155], v[18:19], v[22:23] op_sel_hi:[1,0,1] neg_lo:[0,1,0] neg_hi:[0,1,0]
	v_pk_fma_f32 v[114:115], v[156:157], v[18:19], v[114:115] op_sel_hi:[1,0,1] neg_lo:[0,1,0] neg_hi:[0,1,0]
	ds_read_b128 v[154:157], v6 offset:5440
	v_mov_b32_dpp v18, v13 quad_perm:[3,3,3,3] row_mask:0xf bank_mask:0xf
	s_waitcnt lgkmcnt(11)
	v_pk_fma_f32 v[16:17], v[160:161], v[18:19], v[16:17] op_sel_hi:[1,0,1] neg_lo:[0,1,0] neg_hi:[0,1,0]
	v_pk_fma_f32 v[12:13], v[158:159], v[18:19], v[12:13] op_sel_hi:[1,0,1] neg_lo:[0,1,0] neg_hi:[0,1,0]
	ds_read_b128 v[158:161], v6 offset:5696
	s_waitcnt lgkmcnt(11)
	v_pk_fma_f32 v[104:105], v[164:165], v[18:19], v[114:115] op_sel_hi:[1,0,1] neg_lo:[0,1,0] neg_hi:[0,1,0]
	v_pk_fma_f32 v[22:23], v[162:163], v[18:19], v[22:23] op_sel_hi:[1,0,1] neg_lo:[0,1,0] neg_hi:[0,1,0]
	ds_read_b128 v[162:165], v6 offset:5952
	v_mov_b32_dpp v18, v16 quad_perm:[3,3,3,3] row_mask:0xf bank_mask:0xf
	s_waitcnt lgkmcnt(11)
	v_pk_fma_f32 v[16:17], v[168:169], v[18:19], v[16:17] op_sel_hi:[1,0,1] neg_lo:[0,1,0] neg_hi:[0,1,0]
	v_pk_fma_f32 v[114:115], v[166:167], v[18:19], v[12:13] op_sel_hi:[1,0,1] neg_lo:[0,1,0] neg_hi:[0,1,0]
	ds_read_b128 v[166:169], v6 offset:6208
	s_waitcnt lgkmcnt(11)
	v_pk_fma_f32 v[12:13], v[170:171], v[18:19], v[22:23] op_sel_hi:[1,0,1] neg_lo:[0,1,0] neg_hi:[0,1,0]
	v_pk_fma_f32 v[22:23], v[172:173], v[18:19], v[104:105] op_sel_hi:[1,0,1] neg_lo:[0,1,0] neg_hi:[0,1,0]
	ds_read_b128 v[170:173], v6 offset:6464
	v_mov_b32_dpp v18, v17 quad_perm:[3,3,3,3] row_mask:0xf bank_mask:0xf
	s_waitcnt lgkmcnt(10)
	v_pk_fma_f32 v[12:13], v[178:179], v[18:19], v[12:13] op_sel_hi:[1,0,1] neg_lo:[0,1,0] neg_hi:[0,1,0]
	v_pk_fma_f32 v[22:23], v[180:181], v[18:19], v[22:23] op_sel_hi:[1,0,1] neg_lo:[0,1,0] neg_hi:[0,1,0]
	ds_read_b128 v[178:181], v6 offset:6720
	v_mov_b32_e32 v7, v12
	v_pk_fma_f32 v[2:3], v[174:175], v[18:19], v[114:115] op_sel_hi:[1,0,1] neg_lo:[0,1,0] neg_hi:[0,1,0]
	s_nop 0
	v_mov_b32_dpp v20, v7 quad_perm:[0,0,0,0] row_mask:0xf bank_mask:0xf
	s_waitcnt lgkmcnt(10)
	v_pk_fma_f32 v[12:13], v[182:183], v[20:21], v[12:13] op_sel_hi:[1,0,1] neg_lo:[0,1,0] neg_hi:[0,1,0]
	v_pk_fma_f32 v[22:23], v[184:185], v[20:21], v[22:23] op_sel_hi:[1,0,1] neg_lo:[0,1,0] neg_hi:[0,1,0]
	ds_read_b128 v[182:185], v6 offset:6976
	v_mov_b32_dpp v20, v13 quad_perm:[0,0,0,0] row_mask:0xf bank_mask:0xf
	s_waitcnt lgkmcnt(10)
	v_pk_fma_f32 v[22:23], v[188:189], v[20:21], v[22:23] op_sel_hi:[1,0,1] neg_lo:[0,1,0] neg_hi:[0,1,0]
	v_pk_fma_f32 v[12:13], v[186:187], v[20:21], v[12:13] op_sel_hi:[1,0,1] neg_lo:[0,1,0] neg_hi:[0,1,0]
	ds_read_b128 v[186:189], v6 offset:7232
	v_mov_b32_e32 v20, v131
	v_mov_b32_e32 v7, v22
	s_nop 1
	v_mov_b32_dpp v20, v7 quad_perm:[0,0,0,0] row_mask:0xf bank_mask:0xf
	s_waitcnt lgkmcnt(10)
	v_pk_fma_f32 v[22:23], v[192:193], v[20:21], v[22:23] op_sel_hi:[1,0,1] neg_lo:[0,1,0] neg_hi:[0,1,0]
	v_pk_fma_f32 v[12:13], v[190:191], v[20:21], v[12:13] op_sel_hi:[1,0,1] neg_lo:[0,1,0] neg_hi:[0,1,0]
	ds_read_b128 v[190:193], v6 offset:7488
	v_mov_b32_e32 v20, v131
	v_mov_b32_e32 v7, v23
	s_nop 1
	v_mov_b32_dpp v20, v7 quad_perm:[0,0,0,0] row_mask:0xf bank_mask:0xf
	s_waitcnt lgkmcnt(10)
	v_pk_fma_f32 v[12:13], v[194:195], v[20:21], v[12:13] op_sel_hi:[1,0,1] neg_lo:[0,1,0] neg_hi:[0,1,0]
	v_pk_fma_f32 v[22:23], v[196:197], v[20:21], v[22:23] op_sel_hi:[1,0,1] neg_lo:[0,1,0] neg_hi:[0,1,0]
	ds_read_b128 v[194:197], v6 offset:7744
	v_mov_b32_dpp v20, v12 quad_perm:[1,1,1,1] row_mask:0xf bank_mask:0xf
	s_waitcnt lgkmcnt(10)
	v_pk_fma_f32 v[12:13], v[150:151], v[20:21], v[12:13] op_sel_hi:[1,0,1] neg_lo:[0,1,0] neg_hi:[0,1,0]
	v_pk_fma_f32 v[22:23], v[152:153], v[20:21], v[22:23] op_sel_hi:[1,0,1] neg_lo:[0,1,0] neg_hi:[0,1,0]
	s_nop 0
	v_mov_b32_dpp v20, v13 quad_perm:[1,1,1,1] row_mask:0xf bank_mask:0xf
	s_waitcnt lgkmcnt(9)
	v_pk_fma_f32 v[22:23], v[156:157], v[20:21], v[22:23] op_sel_hi:[1,0,1] neg_lo:[0,1,0] neg_hi:[0,1,0]
	v_pk_fma_f32 v[12:13], v[154:155], v[20:21], v[12:13] op_sel_hi:[1,0,1] neg_lo:[0,1,0] neg_hi:[0,1,0]
	v_mov_b32_e32 v20, v131
	v_mov_b32_e32 v7, v22
	s_nop 1
	v_mov_b32_dpp v20, v7 quad_perm:[1,1,1,1] row_mask:0xf bank_mask:0xf
	s_waitcnt lgkmcnt(8)
	v_pk_fma_f32 v[22:23], v[160:161], v[20:21], v[22:23] op_sel_hi:[1,0,1] neg_lo:[0,1,0] neg_hi:[0,1,0]
	v_pk_fma_f32 v[12:13], v[158:159], v[20:21], v[12:13] op_sel_hi:[1,0,1] neg_lo:[0,1,0] neg_hi:[0,1,0]
	v_mov_b32_e32 v20, v131
	v_mov_b32_e32 v7, v23
	s_nop 1
	v_mov_b32_dpp v20, v7 quad_perm:[1,1,1,1] row_mask:0xf bank_mask:0xf
	s_waitcnt lgkmcnt(7)
	v_pk_fma_f32 v[12:13], v[162:163], v[20:21], v[12:13] op_sel_hi:[1,0,1] neg_lo:[0,1,0] neg_hi:[0,1,0]
	v_pk_fma_f32 v[22:23], v[164:165], v[20:21], v[22:23] op_sel_hi:[1,0,1] neg_lo:[0,1,0] neg_hi:[0,1,0]
	s_nop 0
	v_mov_b32_dpp v20, v12 quad_perm:[2,2,2,2] row_mask:0xf bank_mask:0xf
	s_waitcnt lgkmcnt(6)
	v_pk_fma_f32 v[8:9], v[166:167], v[20:21], v[12:13] op_sel_hi:[1,0,1] neg_lo:[0,1,0] neg_hi:[0,1,0]
	v_mov_b32_e32 v12, v131
	v_mov_b32_e32 v7, v9
	v_pk_fma_f32 v[10:11], v[168:169], v[20:21], v[22:23] op_sel_hi:[1,0,1] neg_lo:[0,1,0] neg_hi:[0,1,0]
	v_mov_b32_e32 v20, v131
	v_mov_b32_dpp v12, v7 quad_perm:[2,2,2,2] row_mask:0xf bank_mask:0xf
	s_waitcnt lgkmcnt(5)
	v_pk_fma_f32 v[10:11], v[172:173], v[12:13], v[10:11] op_sel_hi:[1,0,1] neg_lo:[0,1,0] neg_hi:[0,1,0]
	v_pk_fma_f32 v[8:9], v[170:171], v[12:13], v[8:9] op_sel_hi:[1,0,1] neg_lo:[0,1,0] neg_hi:[0,1,0]
	v_mov_b32_e32 v12, v131
	v_mov_b32_e32 v7, v10
	s_nop 1
	v_mov_b32_dpp v12, v7 quad_perm:[2,2,2,2] row_mask:0xf bank_mask:0xf
	s_waitcnt lgkmcnt(4)
	v_pk_fma_f32 v[22:23], v[180:181], v[12:13], v[10:11] op_sel_hi:[1,0,1] neg_lo:[0,1,0] neg_hi:[0,1,0]
	v_pk_fma_f32 v[8:9], v[178:179], v[12:13], v[8:9] op_sel_hi:[1,0,1] neg_lo:[0,1,0] neg_hi:[0,1,0]
	v_mov_b32_e32 v7, v23
	s_nop 1
	v_mov_b32_dpp v20, v7 quad_perm:[2,2,2,2] row_mask:0xf bank_mask:0xf
	s_waitcnt lgkmcnt(3)
	v_pk_fma_f32 v[102:103], v[182:183], v[20:21], v[8:9] op_sel_hi:[1,0,1] neg_lo:[0,1,0] neg_hi:[0,1,0]
	v_pk_fma_f32 v[22:23], v[184:185], v[20:21], v[22:23] op_sel_hi:[1,0,1] neg_lo:[0,1,0] neg_hi:[0,1,0]
	s_nop 0
	v_mov_b32_dpp v20, v102 quad_perm:[3,3,3,3] row_mask:0xf bank_mask:0xf
	s_waitcnt lgkmcnt(2)
	v_pk_fma_f32 v[100:101], v[188:189], v[20:21], v[22:23] op_sel_hi:[1,0,1] neg_lo:[0,1,0] neg_hi:[0,1,0]
	v_pk_fma_f32 v[22:23], v[186:187], v[20:21], v[102:103] op_sel_hi:[1,0,1] neg_lo:[0,1,0] neg_hi:[0,1,0]
	v_mov_b32_e32 v24, v131
	v_mov_b32_e32 v20, v23
	v_lshlrev_b32_e32 v98, 5, v33
	v_lshl_add_u32 v33, v15, 2, s6
	v_mov_b32_dpp v24, v20 quad_perm:[3,3,3,3] row_mask:0xf bank_mask:0xf
	v_and_b32_e32 v20, -4, v1
	s_waitcnt lgkmcnt(1)
	v_pk_fma_f32 v[12:13], v[192:193], v[24:25], v[100:101] op_sel_hi:[1,0,1] neg_lo:[0,1,0] neg_hi:[0,1,0]
	v_add_u32_e32 v20, 0, v20
	v_mov_b32_e32 v93, v12
	s_waitcnt vmcnt(0)
	v_add_u32_e32 v97, 0x24a00, v20
	v_add_u32_e32 v20, 0x24b00, v20
	ds_read_b32 v97, v97
	ds_read_b32 v99, v20
	v_mov_b32_e32 v20, 0
	v_pk_fma_f32 v[4:5], v[176:177], v[18:19], v[16:17] op_sel_hi:[1,0,1] neg_lo:[0,1,0] neg_hi:[0,1,0]
	v_pk_fma_f32 v[10:11], v[190:191], v[24:25], v[22:23] op_sel_hi:[1,0,1] neg_lo:[0,1,0] neg_hi:[0,1,0]
	v_mov_b32_dpp v20, v93 quad_perm:[3,3,3,3] row_mask:0xf bank_mask:0xf
	v_or_b32_e32 v100, v32, v98
	v_mul_u32_u24_e32 v100, 0x48, v100
	v_add_lshl_u32 v100, v100, v14, 1
	s_waitcnt lgkmcnt(0)
	v_pk_fma_f32 v[8:9], v[196:197], v[20:21], v[12:13] op_sel_hi:[1,0,1] neg_lo:[0,1,0] neg_hi:[0,1,0]
	v_pk_fma_f32 v[6:7], v[194:195], v[20:21], v[10:11] op_sel_hi:[1,0,1] neg_lo:[0,1,0] neg_hi:[0,1,0]
	v_mul_f32_e32 v93, v97, v99
	v_add_u32_e32 v99, 0x18000, v100
	v_add_u32_e32 v100, 0x1a400, v100
	v_mul_f32_e32 v101, v2, v97
	v_mul_f32_e32 v102, v2, v93
	v_cvt_pk_bf16_f32 v101, v101, v102
	ds_write_b16 v99, v101
	ds_write_b16_d16_hi v100, v101
	v_mul_f32_e32 v16, v3, v97
	v_mul_f32_e32 v17, v3, v93
	v_cvt_pk_bf16_f32 v16, v16, v17
	ds_write_b16 v99, v16 offset:144
	ds_write_b16_d16_hi v100, v16 offset:144
	v_mul_f32_e32 v101, v4, v97
	v_mul_f32_e32 v102, v4, v93
	v_cvt_pk_bf16_f32 v101, v101, v102
	ds_write_b16 v99, v101 offset:288
	ds_write_b16_d16_hi v100, v101 offset:288
	v_mul_f32_e32 v16, v5, v97
	v_mul_f32_e32 v17, v5, v93
	v_cvt_pk_bf16_f32 v16, v16, v17
	ds_write_b16 v99, v16 offset:432
	ds_write_b16_d16_hi v100, v16 offset:432
	v_mul_f32_e32 v101, v6, v97
	v_mul_f32_e32 v102, v6, v93
	v_cvt_pk_bf16_f32 v101, v101, v102
	ds_write_b16 v99, v101 offset:2304
	ds_write_b16_d16_hi v100, v101 offset:2304
	v_mul_f32_e32 v16, v7, v97
	v_mul_f32_e32 v17, v7, v93
	v_cvt_pk_bf16_f32 v16, v16, v17
	ds_write_b16 v99, v16 offset:2448
	ds_write_b16_d16_hi v100, v16 offset:2448
	v_mul_f32_e32 v101, v8, v97
	v_mul_f32_e32 v102, v8, v93
	v_cvt_pk_bf16_f32 v101, v101, v102
	ds_write_b16 v99, v101 offset:2592
	ds_write_b16_d16_hi v100, v101 offset:2592
	v_mul_f32_e32 v16, v9, v97
	v_mul_f32_e32 v17, v9, v93
	v_cvt_pk_bf16_f32 v16, v16, v17
	ds_write_b16 v99, v16 offset:2736
	ds_write_b16_d16_hi v100, v16 offset:2736
	s_and_saveexec_b64 s[28:29], vcc
	s_cbranch_execz .Lps_skip
	v_mul_u32_u24_e32 v10, 0x48, v32
	s_movk_i32 s6, 0x90
	v_add_lshl_u32 v10, v10, v14, 1
	v_mad_u32_u24 v18, v32, s6, v33
	v_add_u32_e32 v11, 0x1a400, v10
	v_add_u32_e32 v10, 0x18000, v10
	ds_write_b16 v10, v131
	ds_write_b16 v11, v131
	ds_write_b32 v18, v2
	ds_write_b16 v10, v131 offset:144
	ds_write_b16 v11, v131 offset:144
	ds_write_b32 v18, v3 offset:144
	ds_write_b16 v10, v131 offset:288
	ds_write_b16 v11, v131 offset:288
	ds_write_b32 v18, v4 offset:288
	ds_write_b16 v10, v131 offset:432
	ds_write_b16 v11, v131 offset:432
	ds_write_b32 v18, v5 offset:432
	ds_write_b16 v10, v131 offset:2304
	ds_write_b16 v11, v131 offset:2304
	ds_write_b32 v18, v6 offset:2304
	ds_write_b16 v10, v131 offset:2448
	ds_write_b16 v11, v131 offset:2448
	ds_write_b32 v18, v7 offset:2448
	ds_write_b16 v10, v131 offset:2592
	ds_write_b16 v11, v131 offset:2592
	ds_write_b32 v18, v8 offset:2592
	ds_write_b16 v10, v131 offset:2736
	ds_write_b16 v11, v131 offset:2736
	ds_write_b32 v18, v9 offset:2736
